# bundle: SB ring refill DMAs at loop tail + MLA second-call prologue barrier leaves the 12 Q loads outstanding
# baseline (speedup 1.0000x reference)
; DI f32x16 zero16() { f32x16 z; for (int i = 0; i < 16; ++i) z[i] = 0.f; return z; }
; DI void mla_block(const Params& p, LAS unsigned char* lds, int b, int hd, int qb, int tid) {
;     ...
;     bf16x8 qf[12];
;     {
;         const size_t qrow = tok0 + q0 + r;
; #pragma unroll
;         for (int ks = 0; ks < 8; ++ks) qf[ks] = *(const bf16x8*)(QN + qrow * 512 + hd * 128 + ks * 16 + h * 8);
; #pragma unroll
;         for (int ks = 0; ks < 4; ++ks) qf[8 + ks] = *(const bf16x8*)(QR + qrow * 256 + hd * 64 + ks * 16 + h * 8);
;     }
;     unsigned goff[6];
; #pragma unroll
;     for (int j = 0; j < 6; ++j) {
;         const int pc = wu + 8 * j; goff[j] = 0;
;         if (pc < 25) {
;             const int c = pc * 64 + lane, lr = c / 25; int cc = c - lr * 25; if (cc == 24) cc = 0;
;             const int k32 = lr & 31, key = (lr & 32) + 16 * ((k32 >> 2) & 1) + (k32 & 3) + 4 * (k32 >> 3);
;             const unsigned tok = (unsigned)(b * S_ + key);
;             goff[j] = (cc < 16) ? (unsigned)OFF_KN + (tok * 512u + hd * 128 + cc * 8) * 2u : (unsigned)OFF_PROJ + (tok * 2048u + 1920 + (cc - 16) * 8) * 2u;
;         } else if (pc < 43) {
;             const int c = (pc - 25) * 64 + lane, d = c / 9; int cc = c - d * 9; if (cc == 8) cc = 0;
;             goff[j] = (unsigned)OFF_VMT + ((unsigned)((b * 4 + hd) * 128 + d) * (unsigned)S_ + cc * 8) * 2u;
;         }
;     }
;     const char* wsb = uptr((const char*)p.ws);
;     ...
;     f32x16 o[4]; for (int dt = 0; dt < 4; ++dt) o[dt] = zero16();
;     float m_run = -1e30f, l_run = 0.f;
;     const int ntiles = 4 * qb + 4, wlast = q0 >> 6;
;     __syncthreads();
;     MLA_STAGE(0, 0);
.LBB0_715:
	s_cmp_lt_i32 s1, 43
	s_cselect_b64 s[80:81], -1, 0
	s_cmp_gt_i32 s1, 42
	s_waitcnt vmcnt(12) lgkmcnt(0)
	s_barrier
	s_cbranch_scc1 .LBB0_749
	s_lshl_b32 s2, s1, 10
	s_add_i32 m0, s2, 0
	s_nop 0
	global_load_lds_dwordx4 v166, s[16:17]
	s_cmp_lt_i32 s1, 35
	s_cselect_b64 s[82:83], -1, 0
	s_cmp_gt_i32 s1, 34
	s_cbranch_scc0 .LBB0_750

; #define SB_STAGE(KT, BUF) do { _Pragma("unroll") for (int _j = 0; _j < 3; ++_j) { const int _pc = wu + 8 * _j; if (_pc < 18) { \
;         const unsigned _inc = goff[_j] >= (unsigned)OFF_VST ? 128u : 262144u; \
;         __builtin_amdgcn_global_load_lds((const unsigned*)(wsb + (goff[_j] + (unsigned)(KT) * _inc)), (LAS unsigned*)(lds + (BUF) * SB_BUF + _pc * 1024), 16, 0, 0); } } } while (0)
; #define SB_STAGE(KT, BUF) do { _Pragma("unroll") for (int _j = 0; _j < 3; ++_j) { const int _pc = wu + 8 * _j; if (_pc < 18) { \
;         const unsigned _inc = goff[_j] >= (unsigned)OFF_VST ? 128u : 262144u; \
;         __builtin_amdgcn_global_load_lds((const unsigned*)(wsb + (goff[_j] + (unsigned)(KT) * _inc)), (LAS unsigned*)(lds + (BUF) * SB_BUF + _pc * 1024), 16, 0, 0); } } } while (0)
; DI void sb_block2(const Params& p, LAS unsigned char* lds, int bh, int qb2, int tid) {
;     ...
;         if (it >= 1 && kt - (SB_NB - 1) >= 0) SB_STAGE(kt - (SB_NB - 1), cur == 0 ? SB_NB - 1 : cur - 1);
.LBB0_850:
	s_cmp_gt_i32 s54, 5
	s_cbranch_scc0 .Lsb_tail_nostage
	s_add_i32 s0, s54, -6
	s_mul_i32 s1, s75, 0x4800
	s_add_i32 s1, s1, 0xffffb800
	s_cmp_lg_u32 s75, 0
	s_cselect_b32 s1, s1, 0x1b000
	s_and_b64 vcc, exec, s[4:5]
	s_cbranch_vccnz .Lsb_tail_b
	v_lshl_add_u32 v0, s0, v192, v183
	s_add_i32 m0, s1, s59
	s_nop 0
	global_load_lds_dwordx4 v0, s[84:85]
.Lsb_tail_b:
	s_and_b64 vcc, exec, s[6:7]
	s_cbranch_vccnz .Lsb_tail_c
	v_lshl_add_u32 v0, s0, v193, v187
	s_add_i32 m0, s1, s72
	s_nop 0
	global_load_lds_dwordx4 v0, s[84:85]
.Lsb_tail_c:
	s_and_b64 vcc, exec, s[8:9]
	s_cbranch_vccnz .Lsb_tail_nostage
	v_lshl_add_u32 v0, s0, v194, v186
	s_add_i32 m0, s1, s33
	s_nop 0
	global_load_lds_dwordx4 v0, s[84:85]

; #define SB_STAGE(KT, BUF) do { _Pragma("unroll") for (int _j = 0; _j < 3; ++_j) { const int _pc = wu + 8 * _j; if (_pc < 18) { \
;         const unsigned _inc = goff[_j] >= (unsigned)OFF_VST ? 128u : 262144u; \
;         __builtin_amdgcn_global_load_lds((const unsigned*)(wsb + (goff[_j] + (unsigned)(KT) * _inc)), (LAS unsigned*)(lds + (BUF) * SB_BUF + _pc * 1024), 16, 0, 0); } } } while (0)
; #define SB_STAGE(KT, BUF) do { _Pragma("unroll") for (int _j = 0; _j < 3; ++_j) { const int _pc = wu + 8 * _j; if (_pc < 18) { \
;         const unsigned _inc = goff[_j] >= (unsigned)OFF_VST ? 128u : 262144u; \
;         __builtin_amdgcn_global_load_lds((const unsigned*)(wsb + (goff[_j] + (unsigned)(KT) * _inc)), (LAS unsigned*)(lds + (BUF) * SB_BUF + _pc * 1024), 16, 0, 0); } } } while (0)
; DI void sb_block2(const Params& p, LAS unsigned char* lds, int bh, int qb2, int tid) {
;     ...
;         if (it >= 1 && kt - (SB_NB - 1) >= 0) SB_STAGE(kt - (SB_NB - 1), cur == 0 ? SB_NB - 1 : cur - 1);
.LBB0_904:
	s_cmp_gt_i32 s54, 5
	s_mul_i32 s2, s75, 0x4800
	s_mul_i32 s3, s75, 0x4800
	s_mov_b64 s[0:1], 0
